# mod GEMM epilogue: bias quads loaded once per tile instead of 32 serial load-wait steps
# baseline (speedup 1.0000x reference)
;     __device__ __forceinline__ void operator()(const f32x4 (&acc)[2][2][4][2], const Unit& u, int wr, int wc, int fr, int fq) const {
; #pragma unroll
;         for (int ai = 0; ai < 2; ++ai)
; #pragma unroll
;             for (int m = 0; m < 4; ++m) { const int row = u.pm * 256 + ai * 128 + wr * 64 + m * 16 + fr;
;                 if (row < cfg::NBAT) {
; #pragma unroll
;                     for (int bj = 0; bj < 2; ++bj)
; #pragma unroll
;                         for (int n = 0; n < 2; ++n) { const int col = u.pn * 256 + bj * 128 + wc * 32 + 8 * fq + 4 * n;
;                             *(f32x4*)(MOD + (size_t)row * cfg::NMOD + col) = acc[ai][bj][m][n] + *(const f32x4*)(bada + col); } } }
.LBB0_148:
	s_lshl_b32 s11, s20, 8
	v_add_u32_e32 v154, s11, v96
	s_movk_i32 s13, 0x88
	v_cmp_gt_i32_e32 vcc, s13, v154
	v_lshl_or_b32 v142, s18, 8, v145
	v_ashrrev_i32_e32 v143, 31, v142
	v_lshlrev_b64 v[252:253], 2, v[142:143]
	v_lshl_add_u64 v[252:253], s[2:3], 0, v[252:253]
	global_load_dwordx4 v[236:239], v[252:253], off
	global_load_dwordx4 v[240:243], v[252:253], off offset:16
	global_load_dwordx4 v[244:247], v[252:253], off offset:512
	global_load_dwordx4 v[248:251], v[252:253], off offset:528
	s_waitcnt vmcnt(0)
	s_and_saveexec_b64 s[18:19], vcc
	s_mov_b32 s72, 0xa00000
	s_mov_b32 s46, 0xe00000
	s_mov_b32 s60, 0x1000000
	s_mov_b32 s70, 0x1200000
	s_mov_b32 s71, 0x1400000
	s_cbranch_execz .LBB0_150
	v_ashrrev_i32_e32 v143, 31, v142
	v_lshlrev_b64 v[146:147], 2, v[142:143]
	v_lshl_add_u64 v[148:149], s[2:3], 0, v[146:147]
	s_nop 1
	v_mov_b64_e32 v[156:157], v[236:237]
	v_mov_b64_e32 v[158:159], v[238:239]
	s_mov_b32 s13, 0x18000
	v_pk_add_f32 v[126:127], v[126:127], v[156:157]
	v_mov_b64_e32 v[156:157], s[36:37]
	v_mad_i64_i32 v[156:157], s[22:23], v154, s13, v[156:157]
	v_pk_add_f32 v[128:129], v[128:129], v[158:159]
	v_lshl_add_u64 v[146:147], v[156:157], 0, v[146:147]
	global_store_dwordx4 v[146:147], v[126:129], off
	s_nop 1
	v_mov_b64_e32 v[126:127], v[240:241]
	v_mov_b64_e32 v[128:129], v[242:243]
	v_pk_add_f32 v[124:125], v[124:125], v[128:129]
	v_pk_add_f32 v[122:123], v[122:123], v[126:127]
	global_store_dwordx4 v[146:147], v[122:125], off offset:16
	s_nop 1
	v_mov_b64_e32 v[122:123], v[244:245]
	v_mov_b64_e32 v[124:125], v[246:247]
	v_pk_add_f32 v[120:121], v[120:121], v[124:125]
	v_pk_add_f32 v[118:119], v[118:119], v[122:123]
	global_store_dwordx4 v[146:147], v[118:121], off offset:512
	s_nop 1
	v_mov_b64_e32 v[118:119], v[248:249]
	v_mov_b64_e32 v[120:121], v[250:251]
	v_pk_add_f32 v[112:113], v[112:113], v[120:121]
	v_pk_add_f32 v[110:111], v[110:111], v[118:119]
	global_store_dwordx4 v[146:147], v[110:113], off offset:528
.LBB0_150:
	s_or_b64 exec, exec, s[18:19]
	s_nop 0
	v_add_u32_e32 v110, s11, v150
	s_movk_i32 s13, 0x88
	v_cmp_gt_i32_e32 vcc, s13, v110
	s_and_saveexec_b64 s[18:19], vcc
	s_cbranch_execz .LBB0_152
	v_ashrrev_i32_e32 v143, 31, v142
	v_lshlrev_b64 v[112:113], 2, v[142:143]
	v_lshl_add_u64 v[122:123], s[2:3], 0, v[112:113]
	s_nop 1
	v_mov_b64_e32 v[118:119], v[236:237]
	v_mov_b64_e32 v[120:121], v[238:239]
	s_mov_b32 s13, 0x18000
	v_pk_add_f32 v[114:115], v[114:115], v[118:119]
	v_mov_b64_e32 v[118:119], s[36:37]
	v_mad_i64_i32 v[110:111], s[22:23], v110, s13, v[118:119]
	v_pk_add_f32 v[116:117], v[116:117], v[120:121]
	v_lshl_add_u64 v[118:119], v[110:111], 0, v[112:113]
	global_store_dwordx4 v[118:119], v[114:117], off
	s_nop 1
	v_mov_b64_e32 v[110:111], v[240:241]
	v_mov_b64_e32 v[112:113], v[242:243]
	v_pk_add_f32 v[108:109], v[108:109], v[112:113]
	v_pk_add_f32 v[106:107], v[106:107], v[110:111]
	global_store_dwordx4 v[118:119], v[106:109], off offset:16
	s_nop 1
	v_mov_b64_e32 v[106:107], v[244:245]
	v_mov_b64_e32 v[108:109], v[246:247]
	v_pk_add_f32 v[104:105], v[104:105], v[108:109]
	v_pk_add_f32 v[102:103], v[102:103], v[106:107]
	global_store_dwordx4 v[118:119], v[102:105], off offset:512
	s_nop 1
	v_mov_b64_e32 v[102:103], v[248:249]
	v_mov_b64_e32 v[104:105], v[250:251]
	v_pk_add_f32 v[94:95], v[94:95], v[104:105]
	v_pk_add_f32 v[92:93], v[92:93], v[102:103]
	global_store_dwordx4 v[118:119], v[92:95], off offset:528
.LBB0_152:
	s_or_b64 exec, exec, s[18:19]
	s_nop 0
	v_add_u32_e32 v92, s11, v151
	s_movk_i32 s13, 0x88
	v_cmp_gt_i32_e32 vcc, s13, v92
	s_and_saveexec_b64 s[18:19], vcc
	s_mov_b32 s75, 0x400000
	s_mov_b32 s74, 0x600000
	s_mov_b32 s73, 0xc00000
	s_cbranch_execz .LBB0_154
	v_ashrrev_i32_e32 v143, 31, v142
	v_lshlrev_b64 v[94:95], 2, v[142:143]
	v_lshl_add_u64 v[106:107], s[2:3], 0, v[94:95]
	s_nop 1
	v_mov_b64_e32 v[102:103], v[236:237]
	v_mov_b64_e32 v[104:105], v[238:239]
	s_mov_b32 s13, 0x18000
	v_pk_add_f32 v[98:99], v[98:99], v[102:103]
	v_mov_b64_e32 v[102:103], s[36:37]
	v_mad_i64_i32 v[92:93], s[22:23], v92, s13, v[102:103]
	v_pk_add_f32 v[100:101], v[100:101], v[104:105]
	v_lshl_add_u64 v[102:103], v[92:93], 0, v[94:95]
	global_store_dwordx4 v[102:103], v[98:101], off
	s_nop 1
	v_mov_b64_e32 v[92:93], v[240:241]
	v_mov_b64_e32 v[94:95], v[242:243]
	v_pk_add_f32 v[90:91], v[90:91], v[94:95]
	v_pk_add_f32 v[88:89], v[88:89], v[92:93]
	global_store_dwordx4 v[102:103], v[88:91], off offset:16
	s_nop 1
	v_mov_b64_e32 v[88:89], v[244:245]
	v_mov_b64_e32 v[90:91], v[246:247]
	v_pk_add_f32 v[86:87], v[86:87], v[90:91]
	v_pk_add_f32 v[84:85], v[84:85], v[88:89]
	global_store_dwordx4 v[102:103], v[84:87], off offset:512
	s_nop 1
	v_mov_b64_e32 v[84:85], v[248:249]
	v_mov_b64_e32 v[86:87], v[250:251]
	v_pk_add_f32 v[78:79], v[78:79], v[86:87]
	v_pk_add_f32 v[76:77], v[76:77], v[84:85]
	global_store_dwordx4 v[102:103], v[76:79], off offset:528
.LBB0_154:
	s_or_b64 exec, exec, s[18:19]
	s_nop 0
	v_add_u32_e32 v76, s11, v152
	s_movk_i32 s11, 0x88
	v_cmp_gt_i32_e32 vcc, s11, v76
	s_and_saveexec_b64 s[18:19], vcc
	s_cbranch_execz .LBB0_156
	v_ashrrev_i32_e32 v143, 31, v142
	v_lshlrev_b64 v[78:79], 2, v[142:143]
	v_lshl_add_u64 v[88:89], s[2:3], 0, v[78:79]
	s_nop 1
	v_mov_b64_e32 v[84:85], v[236:237]
	v_mov_b64_e32 v[86:87], v[238:239]
	s_mov_b32 s11, 0x18000
	v_pk_add_f32 v[80:81], v[80:81], v[84:85]
	v_mov_b64_e32 v[84:85], s[36:37]
	v_mad_i64_i32 v[76:77], s[22:23], v76, s11, v[84:85]
	v_pk_add_f32 v[82:83], v[82:83], v[86:87]
	v_lshl_add_u64 v[84:85], v[76:77], 0, v[78:79]
	global_store_dwordx4 v[84:85], v[80:83], off
	s_nop 1
	v_mov_b64_e32 v[76:77], v[240:241]
	v_mov_b64_e32 v[78:79], v[242:243]
	v_pk_add_f32 v[74:75], v[74:75], v[78:79]
	v_pk_add_f32 v[72:73], v[72:73], v[76:77]
	global_store_dwordx4 v[84:85], v[72:75], off offset:16
	s_nop 1
	v_mov_b64_e32 v[72:73], v[244:245]
	v_mov_b64_e32 v[74:75], v[246:247]
	v_pk_add_f32 v[70:71], v[70:71], v[74:75]
	v_pk_add_f32 v[68:69], v[68:69], v[72:73]
	global_store_dwordx4 v[84:85], v[68:71], off offset:512
	s_nop 1
	v_mov_b64_e32 v[68:69], v[248:249]
	v_mov_b64_e32 v[70:71], v[250:251]
	v_pk_add_f32 v[66:67], v[66:67], v[70:71]
	v_pk_add_f32 v[64:65], v[64:65], v[68:69]
	global_store_dwordx4 v[84:85], v[64:67], off offset:528
;     __device__ __forceinline__ void operator()(const f32x4 (&acc)[2][2][4][2], const Unit& u, int wr, int wc, int fr, int fq) const {
; #pragma unroll
;         for (int ai = 0; ai < 2; ++ai)
; #pragma unroll
;             for (int m = 0; m < 4; ++m) { const int row = u.pm * 256 + ai * 128 + wr * 64 + m * 16 + fr;
;                 if (row < cfg::NBAT) {
; #pragma unroll
;                     for (int bj = 0; bj < 2; ++bj)
; #pragma unroll
;                         for (int n = 0; n < 2; ++n) { const int col = u.pn * 256 + bj * 128 + wc * 32 + 8 * fq + 4 * n;
;                             *(f32x4*)(MOD + (size_t)row * cfg::NMOD + col) = acc[ai][bj][m][n] + *(const f32x4*)(bada + col); } } }
.LBB0_156:
	s_or_b64 exec, exec, s[18:19]
	s_nop 0
	v_add_u32_e32 v64, 0x80, v154
	s_movk_i32 s11, 0x88
	v_cmp_gt_i32_e32 vcc, s11, v64
	s_and_saveexec_b64 s[18:19], vcc
	s_cbranch_execz .LBB0_158
	v_ashrrev_i32_e32 v143, 31, v142
	v_lshlrev_b64 v[70:71], 2, v[142:143]
	v_lshl_add_u64 v[72:73], s[2:3], 0, v[70:71]
	s_nop 1
	v_mov_b64_e32 v[66:67], v[236:237]
	v_mov_b64_e32 v[68:69], v[238:239]
	s_mov_b32 s11, 0x18000
	v_pk_add_f32 v[60:61], v[60:61], v[66:67]
	v_mov_b64_e32 v[66:67], s[36:37]
	v_mad_i64_i32 v[64:65], s[22:23], v64, s11, v[66:67]
	v_pk_add_f32 v[62:63], v[62:63], v[68:69]
	v_lshl_add_u64 v[64:65], v[64:65], 0, v[70:71]
	global_store_dwordx4 v[64:65], v[60:63], off
	s_nop 1
	v_mov_b64_e32 v[60:61], v[240:241]
	v_mov_b64_e32 v[62:63], v[242:243]
	v_pk_add_f32 v[58:59], v[58:59], v[62:63]
	v_pk_add_f32 v[56:57], v[56:57], v[60:61]
	global_store_dwordx4 v[64:65], v[56:59], off offset:16
	s_nop 1
	v_mov_b64_e32 v[56:57], v[244:245]
	v_mov_b64_e32 v[58:59], v[246:247]
	v_pk_add_f32 v[54:55], v[54:55], v[58:59]
	v_pk_add_f32 v[52:53], v[52:53], v[56:57]
	global_store_dwordx4 v[64:65], v[52:55], off offset:512
	s_nop 1
	v_mov_b64_e32 v[52:53], v[248:249]
	v_mov_b64_e32 v[54:55], v[250:251]
	v_pk_add_f32 v[46:47], v[46:47], v[54:55]
	v_pk_add_f32 v[44:45], v[44:45], v[52:53]
	global_store_dwordx4 v[64:65], v[44:47], off offset:528
.LBB0_158:
	s_or_b64 exec, exec, s[18:19]
	s_nop 0
	v_add_u32_e32 v44, 0x90, v154
	s_movk_i32 s11, 0x88
	v_cmp_gt_i32_e32 vcc, s11, v44
	s_and_saveexec_b64 s[18:19], vcc
	s_cbranch_execz .LBB0_160
	v_ashrrev_i32_e32 v143, 31, v142
	v_lshlrev_b64 v[46:47], 2, v[142:143]
	v_lshl_add_u64 v[56:57], s[2:3], 0, v[46:47]
	s_nop 1
	v_mov_b64_e32 v[52:53], v[236:237]
	v_mov_b64_e32 v[54:55], v[238:239]
	s_mov_b32 s11, 0x18000
	v_pk_add_f32 v[48:49], v[48:49], v[52:53]
	v_mov_b64_e32 v[52:53], s[36:37]
	v_mad_i64_i32 v[44:45], s[22:23], v44, s11, v[52:53]
	v_pk_add_f32 v[50:51], v[50:51], v[54:55]
	v_lshl_add_u64 v[52:53], v[44:45], 0, v[46:47]
	global_store_dwordx4 v[52:53], v[48:51], off
	s_nop 1
	v_mov_b64_e32 v[44:45], v[240:241]
	v_mov_b64_e32 v[46:47], v[242:243]
	v_pk_add_f32 v[42:43], v[42:43], v[46:47]
	v_pk_add_f32 v[40:41], v[40:41], v[44:45]
	global_store_dwordx4 v[52:53], v[40:43], off offset:16
	s_nop 1
	v_mov_b64_e32 v[40:41], v[244:245]
	v_mov_b64_e32 v[42:43], v[246:247]
	v_pk_add_f32 v[38:39], v[38:39], v[42:43]
	v_pk_add_f32 v[36:37], v[36:37], v[40:41]
	global_store_dwordx4 v[52:53], v[36:39], off offset:512
	s_nop 1
	v_mov_b64_e32 v[36:37], v[248:249]
	v_mov_b64_e32 v[38:39], v[250:251]
	v_pk_add_f32 v[30:31], v[30:31], v[38:39]
	v_pk_add_f32 v[28:29], v[28:29], v[36:37]
	global_store_dwordx4 v[52:53], v[28:31], off offset:528
.LBB0_160:
	s_or_b64 exec, exec, s[18:19]
	s_nop 0
	v_add_u32_e32 v28, 0xa0, v154
	s_movk_i32 s11, 0x88
	v_cmp_gt_i32_e32 vcc, s11, v28
	s_and_saveexec_b64 s[18:19], vcc
	s_cbranch_execz .LBB0_162
	v_ashrrev_i32_e32 v143, 31, v142
	v_lshlrev_b64 v[30:31], 2, v[142:143]
	v_lshl_add_u64 v[40:41], s[2:3], 0, v[30:31]
	s_nop 1
	v_mov_b64_e32 v[36:37], v[236:237]
	v_mov_b64_e32 v[38:39], v[238:239]
	s_mov_b32 s11, 0x18000
	v_pk_add_f32 v[32:33], v[32:33], v[36:37]
	v_mov_b64_e32 v[36:37], s[36:37]
	v_mad_i64_i32 v[28:29], s[22:23], v28, s11, v[36:37]
	v_pk_add_f32 v[34:35], v[34:35], v[38:39]
	v_lshl_add_u64 v[36:37], v[28:29], 0, v[30:31]
	global_store_dwordx4 v[36:37], v[32:35], off
	s_nop 1
	v_mov_b64_e32 v[28:29], v[240:241]
	v_mov_b64_e32 v[30:31], v[242:243]
	v_pk_add_f32 v[26:27], v[26:27], v[30:31]
	v_pk_add_f32 v[24:25], v[24:25], v[28:29]
	global_store_dwordx4 v[36:37], v[24:27], off offset:16
	s_nop 1
	v_mov_b64_e32 v[24:25], v[244:245]
	v_mov_b64_e32 v[26:27], v[246:247]
	v_pk_add_f32 v[22:23], v[22:23], v[26:27]
	v_pk_add_f32 v[20:21], v[20:21], v[24:25]
	global_store_dwordx4 v[36:37], v[20:23], off offset:512
	s_nop 1
	v_mov_b64_e32 v[20:21], v[248:249]
	v_mov_b64_e32 v[22:23], v[250:251]
	v_pk_add_f32 v[14:15], v[14:15], v[22:23]
	v_pk_add_f32 v[12:13], v[12:13], v[20:21]
	global_store_dwordx4 v[36:37], v[12:15], off offset:528
.LBB0_162:
	s_or_b64 exec, exec, s[18:19]
	s_nop 0
	v_add_u32_e32 v12, 0xb0, v154
	s_movk_i32 s11, 0x88
	v_cmp_gt_i32_e32 vcc, s11, v12
	s_and_saveexec_b64 s[18:19], vcc
	s_cbranch_execz .LBB0_164
	v_ashrrev_i32_e32 v143, 31, v142
	v_lshlrev_b64 v[14:15], 2, v[142:143]
	v_lshl_add_u64 v[24:25], s[2:3], 0, v[14:15]
	s_nop 1
	v_mov_b64_e32 v[20:21], v[236:237]
	v_mov_b64_e32 v[22:23], v[238:239]
	s_mov_b32 s11, 0x18000
	v_pk_add_f32 v[16:17], v[16:17], v[20:21]
	v_mov_b64_e32 v[20:21], s[36:37]
	v_mad_i64_i32 v[12:13], s[22:23], v12, s11, v[20:21]
	v_pk_add_f32 v[18:19], v[18:19], v[22:23]
	v_lshl_add_u64 v[20:21], v[12:13], 0, v[14:15]
	global_store_dwordx4 v[20:21], v[16:19], off
	s_nop 1
	v_mov_b64_e32 v[12:13], v[240:241]
	v_mov_b64_e32 v[14:15], v[242:243]
	v_pk_add_f32 v[10:11], v[10:11], v[14:15]
	v_pk_add_f32 v[8:9], v[8:9], v[12:13]
	global_store_dwordx4 v[20:21], v[8:11], off offset:16
	s_nop 1
	v_mov_b64_e32 v[8:9], v[244:245]
	v_mov_b64_e32 v[10:11], v[246:247]
	v_pk_add_f32 v[6:7], v[6:7], v[10:11]
	v_pk_add_f32 v[4:5], v[4:5], v[8:9]
	global_store_dwordx4 v[20:21], v[4:7], off offset:512
	s_nop 1
	v_mov_b64_e32 v[4:5], v[248:249]
	v_mov_b64_e32 v[6:7], v[250:251]
	v_pk_add_f32 v[2:3], v[2:3], v[6:7]
	v_pk_add_f32 v[0:1], v[0:1], v[4:5]
	global_store_dwordx4 v[20:21], v[0:3], off offset:528
